# v55 plus 8 of the SwiGLU epilogue gate*up multiply pairs packed into v_pk_mul_f32
# baseline (speedup 1.0000x reference)
; __device__ __forceinline__ unsigned cvt_pk_bf16(float lo, float hi) { unsigned r; asm volatile("v_cvt_pk_bf16_f32 %0, %1, %2" : "=v"(r) : "v"(lo), "v"(hi)); return r; }
; __device__ __forceinline__ float silu_mul(float g, float u) { const float e = __builtin_amdgcn_exp2f(-1.4426950408889634f * g); return g * u * __builtin_amdgcn_rcpf(1.0f + e); }
;     __device__ __forceinline__ void operator()(const f32x4 (&acc)[2][2][4][2], const Unit& u, int wr, int wc, int fr_, int fq_) const {
;     ...
;         const int row0 = u.pm * BM + wr * 64 + fr, col0 = u.pn * HALF + wc * 32 + 8 * fq;
; #pragma unroll
;         for (int ai = 0; ai < 2; ++ai)
; #pragma unroll
;             for (int m = 0; m < 4; ++m) {
;                 bf16_t* rowp = O + (size_t)(row0 + ai * HALF + m * 16) * ldc + col0;
;                 const f32x4 g0 = acc[ai][0][m][0], g1 = acc[ai][0][m][1], u0 = acc[ai][1][m][0], u1 = acc[ai][1][m][1];
;                 u32x4 w;
;                 w.x = cvt_pk_bf16(silu_mul(g0[0], u0[0]), silu_mul(g0[1], u0[1])); w.y = cvt_pk_bf16(silu_mul(g0[2], u0[2]), silu_mul(g0[3], u0[3]));
;                 w.z = cvt_pk_bf16(silu_mul(g1[0], u1[0]), silu_mul(g1[1], u1[1])); w.w = cvt_pk_bf16(silu_mul(g1[2], u1[2]), silu_mul(g1[3], u1[3]));
;                 st16(rowp, w);
.LBB0_405:
	v_mul_f32_e32 v149, 0xbfb8aa3b, v130
	v_exp_f32_e32 v149, v149
	v_mul_f32_e32 v126, v130, v126
	v_mul_f32_e32 v127, v131, v127
	v_mov_b32_e32 v144, v219
	v_add_f32_e32 v130, 1.0, v149
	v_rcp_f32_e32 v130, v130
	v_pk_mul_f32 v[128:129], v[132:133], v[128:129]
	v_mul_f32_e32 v126, v130, v126
	v_mul_f32_e32 v130, 0xbfb8aa3b, v131
	v_exp_f32_e32 v130, v130
	v_mul_f32_e32 v118, v122, v118
	v_mul_f32_e32 v119, v123, v119
	v_mul_f32_e32 v110, v114, v110
	v_add_f32_e32 v130, 1.0, v130
	v_rcp_f32_e32 v130, v130
	s_lshl_b32 s4, s20, 7
	v_lshrrev_b32_e32 v145, 1, v144
	v_and_or_b32 v145, v145, 24, s4
	v_mul_f32_e32 v127, v130, v127
	v_cvt_pk_bf16_f32 v126, v126, v127
	v_mul_f32_e32 v127, 0xbfb8aa3b, v132
	v_exp_f32_e32 v127, v127
	v_or_b32_e32 v146, s86, v145
	v_and_or_b32 v144, v144, 15, s77
	v_lshl_add_u32 v148, s3, 8, v144
	v_add_f32_e32 v127, 1.0, v127
	v_rcp_f32_e32 v127, v127
	v_ashrrev_i32_e32 v147, 31, v146
	v_mov_b64_e32 v[144:145], s[82:83]
	v_mad_i64_i32 v[150:151], s[4:5], v148, s22, v[144:145]
	v_mul_f32_e32 v127, v127, v128
	v_mul_f32_e32 v128, 0xbfb8aa3b, v133
	v_exp_f32_e32 v128, v128
	v_lshlrev_b64 v[146:147], 1, v[146:147]
	v_mul_f32_e32 v111, v115, v111
	v_lshl_add_u64 v[150:151], v[150:151], 0, v[146:147]
	v_add_f32_e32 v128, 1.0, v128
	v_rcp_f32_e32 v128, v128
	v_pk_mul_f32 v[112:113], v[116:117], v[112:113]
	v_mul_f32_e32 v102, v106, v102
	v_mul_f32_e32 v128, v128, v129
	v_cvt_pk_bf16_f32 v127, v127, v128
	v_mul_f32_e32 v128, 0xbfb8aa3b, v122
	v_exp_f32_e32 v128, v128
	v_mul_f32_e32 v103, v107, v103
	v_mul_f32_e32 v94, v98, v94
	v_mul_f32_e32 v95, v99, v95
	v_add_f32_e32 v122, 1.0, v128
	v_rcp_f32_e32 v122, v122
	v_pk_mul_f32 v[96:97], v[100:101], v[96:97]
	v_mul_f32_e32 v86, v90, v86
	v_mul_f32_e32 v118, v122, v118
	v_mul_f32_e32 v122, 0xbfb8aa3b, v123
	v_exp_f32_e32 v122, v122
	v_mul_f32_e32 v87, v91, v87
	v_mul_f32_e32 v78, v82, v78
	v_mul_f32_e32 v79, v83, v79
	v_add_f32_e32 v122, 1.0, v122
	v_rcp_f32_e32 v122, v122
	v_pk_mul_f32 v[80:81], v[84:85], v[80:81]
	v_mul_f32_e32 v70, v74, v70
	v_mul_f32_e32 v119, v122, v119
	v_cvt_pk_bf16_f32 v128, v118, v119
	v_mul_f32_e32 v118, 0xbfb8aa3b, v124
	v_exp_f32_e32 v118, v118
	v_mul_f32_e32 v119, v124, v120
	v_mul_f32_e32 v120, v125, v121
	v_mul_f32_e32 v71, v75, v71
	v_add_f32_e32 v118, 1.0, v118
	v_rcp_f32_e32 v118, v118
	v_mul_f32_e32 v62, v66, v62
	v_mul_f32_e32 v63, v67, v63
	v_mul_f32_e32 v118, v118, v119
	v_mul_f32_e32 v119, 0xbfb8aa3b, v125
	v_exp_f32_e32 v119, v119
	v_pk_mul_f32 v[64:65], v[68:69], v[64:65]
	v_mul_f32_e32 v54, v58, v54
	v_mul_f32_e32 v55, v59, v55
	v_add_f32_e32 v119, 1.0, v119
	v_rcp_f32_e32 v119, v119
	v_mul_f32_e32 v46, v50, v46
	v_mul_f32_e32 v47, v51, v47
	v_mul_f32_e32 v119, v119, v120
	v_mul_f32_e32 v120, 0xbfb8aa3b, v114
	v_exp_f32_e32 v120, v120
	v_cvt_pk_bf16_f32 v129, v118, v119
	global_store_dwordx4 v[150:151], v[126:129], off
	v_or_b32_e32 v118, 16, v148
	v_add_f32_e32 v114, 1.0, v120
	v_rcp_f32_e32 v114, v114
	v_mad_i64_i32 v[118:119], s[4:5], v118, s22, v[144:145]
	v_lshl_add_u64 v[118:119], v[118:119], 0, v[146:147]
	v_mul_f32_e32 v110, v114, v110
	v_mul_f32_e32 v114, 0xbfb8aa3b, v115
	v_exp_f32_e32 v114, v114
	v_pk_mul_f32 v[48:49], v[52:53], v[48:49]
	v_mul_f32_e32 v38, v42, v38
	v_mul_f32_e32 v39, v43, v39
	v_add_f32_e32 v114, 1.0, v114
	v_rcp_f32_e32 v114, v114
	v_mul_f32_e32 v30, v34, v30
	v_mul_f32_e32 v31, v35, v31
	v_mul_f32_e32 v111, v114, v111
	v_cvt_pk_bf16_f32 v110, v110, v111
	v_mul_f32_e32 v111, 0xbfb8aa3b, v116
	v_exp_f32_e32 v111, v111
	v_pk_mul_f32 v[32:33], v[36:37], v[32:33]
	v_mul_f32_e32 v22, v26, v22
	v_mul_f32_e32 v23, v27, v23
	v_add_f32_e32 v111, 1.0, v111
	v_rcp_f32_e32 v111, v111
	v_mul_f32_e32 v10, v18, v10
	v_mul_f32_e32 v11, v19, v11
	v_mul_f32_e32 v111, v111, v112
	v_mul_f32_e32 v112, 0xbfb8aa3b, v117
	v_exp_f32_e32 v112, v112
	v_pk_mul_f32 v[12:13], v[20:21], v[12:13]
	v_mul_f32_e32 v2, v6, v2
	v_mul_f32_e32 v3, v7, v3
	v_add_f32_e32 v112, 1.0, v112
	v_rcp_f32_e32 v112, v112
	s_and_b64 vcc, exec, s[6:7]
	v_mul_f32_e32 v112, v112, v113
	v_cvt_pk_bf16_f32 v111, v111, v112
	v_mul_f32_e32 v112, 0xbfb8aa3b, v106
	v_exp_f32_e32 v112, v112
	s_nop 0
	v_add_f32_e32 v106, 1.0, v112
	v_rcp_f32_e32 v106, v106
	s_nop 0
	v_mul_f32_e32 v102, v106, v102
	v_mul_f32_e32 v106, 0xbfb8aa3b, v107
	v_exp_f32_e32 v106, v106
	s_nop 0
	v_add_f32_e32 v106, 1.0, v106
	v_rcp_f32_e32 v106, v106
	s_nop 0
	v_mul_f32_e32 v103, v106, v103
	v_cvt_pk_bf16_f32 v112, v102, v103
	v_mul_f32_e32 v102, 0xbfb8aa3b, v108
	v_exp_f32_e32 v102, v102
	v_mul_f32_e32 v103, v108, v104
	v_mul_f32_e32 v104, v109, v105
	v_add_f32_e32 v102, 1.0, v102
	v_rcp_f32_e32 v102, v102
	s_nop 0
	v_mul_f32_e32 v102, v102, v103
	v_mul_f32_e32 v103, 0xbfb8aa3b, v109
	v_exp_f32_e32 v103, v103
	s_nop 0
	v_add_f32_e32 v103, 1.0, v103
	v_rcp_f32_e32 v103, v103
	s_nop 0
	v_mul_f32_e32 v103, v103, v104
	v_mul_f32_e32 v104, 0xbfb8aa3b, v98
	v_exp_f32_e32 v104, v104
	v_cvt_pk_bf16_f32 v113, v102, v103
	global_store_dwordx4 v[118:119], v[110:113], off
	v_or_b32_e32 v102, 32, v148
	v_add_f32_e32 v98, 1.0, v104
	v_rcp_f32_e32 v98, v98
	v_mad_i64_i32 v[102:103], s[4:5], v102, s22, v[144:145]
	v_lshl_add_u64 v[102:103], v[102:103], 0, v[146:147]
	v_mul_f32_e32 v94, v98, v94
	v_mul_f32_e32 v98, 0xbfb8aa3b, v99
	v_exp_f32_e32 v98, v98
	s_nop 0
	v_add_f32_e32 v98, 1.0, v98
	v_rcp_f32_e32 v98, v98
	s_nop 0
	v_mul_f32_e32 v95, v98, v95
	v_cvt_pk_bf16_f32 v94, v94, v95
	v_mul_f32_e32 v95, 0xbfb8aa3b, v100
	v_exp_f32_e32 v95, v95
	s_nop 0
	v_add_f32_e32 v95, 1.0, v95
	v_rcp_f32_e32 v95, v95
	s_nop 0
	v_mul_f32_e32 v95, v95, v96
	v_mul_f32_e32 v96, 0xbfb8aa3b, v101
	v_exp_f32_e32 v96, v96
; __device__ __forceinline__ unsigned cvt_pk_bf16(float lo, float hi) { unsigned r; asm volatile("v_cvt_pk_bf16_f32 %0, %1, %2" : "=v"(r) : "v"(lo), "v"(hi)); return r; }
; __device__ __forceinline__ float silu_mul(float g, float u) { const float e = __builtin_amdgcn_exp2f(-1.4426950408889634f * g); return g * u * __builtin_amdgcn_rcpf(1.0f + e); }
;     __device__ __forceinline__ void operator()(const f32x4 (&acc)[2][2][4][2], const Unit& u, int wr, int wc, int fr_, int fq_) const {
;     ...
;             for (int m = 0; m < 4; ++m) {
;                 bf16_t* rowp = O + (size_t)(row0 + ai * HALF + m * 16) * ldc + col0;
;                 const f32x4 g0 = acc[ai][0][m][0], g1 = acc[ai][0][m][1], u0 = acc[ai][1][m][0], u1 = acc[ai][1][m][1];
;                 u32x4 w;
;                 w.x = cvt_pk_bf16(silu_mul(g0[0], u0[0]), silu_mul(g0[1], u0[1])); w.y = cvt_pk_bf16(silu_mul(g0[2], u0[2]), silu_mul(g0[3], u0[3]));
;                 w.z = cvt_pk_bf16(silu_mul(g1[0], u1[0]), silu_mul(g1[1], u1[1])); w.w = cvt_pk_bf16(silu_mul(g1[2], u1[2]), silu_mul(g1[3], u1[3]));
;                 st16(rowp, w);
	s_nop 0
	v_add_f32_e32 v96, 1.0, v96
	v_rcp_f32_e32 v96, v96
	s_nop 0
	v_mul_f32_e32 v96, v96, v97
	v_cvt_pk_bf16_f32 v95, v95, v96
	v_mul_f32_e32 v96, 0xbfb8aa3b, v90
	v_exp_f32_e32 v96, v96
	s_nop 0
	v_add_f32_e32 v90, 1.0, v96
	v_rcp_f32_e32 v90, v90
	s_nop 0
	v_mul_f32_e32 v86, v90, v86
	v_mul_f32_e32 v90, 0xbfb8aa3b, v91
	v_exp_f32_e32 v90, v90
	s_nop 0
	v_add_f32_e32 v90, 1.0, v90
	v_rcp_f32_e32 v90, v90
	s_nop 0
	v_mul_f32_e32 v87, v90, v87
	v_cvt_pk_bf16_f32 v96, v86, v87
	v_mul_f32_e32 v86, 0xbfb8aa3b, v92
	v_exp_f32_e32 v86, v86
	v_mul_f32_e32 v87, v92, v88
	v_mul_f32_e32 v88, v93, v89
	v_add_f32_e32 v86, 1.0, v86
	v_rcp_f32_e32 v86, v86
	s_nop 0
	v_mul_f32_e32 v86, v86, v87
	v_mul_f32_e32 v87, 0xbfb8aa3b, v93
	v_exp_f32_e32 v87, v87
	s_nop 0
	v_add_f32_e32 v87, 1.0, v87
	v_rcp_f32_e32 v87, v87
	s_nop 0
	v_mul_f32_e32 v87, v87, v88
	v_mul_f32_e32 v88, 0xbfb8aa3b, v82
	v_exp_f32_e32 v88, v88
	v_cvt_pk_bf16_f32 v97, v86, v87
	global_store_dwordx4 v[102:103], v[94:97], off
	v_or_b32_e32 v86, 48, v148
	v_add_f32_e32 v82, 1.0, v88
	v_rcp_f32_e32 v82, v82
	v_mad_i64_i32 v[86:87], s[4:5], v86, s22, v[144:145]
	v_lshl_add_u64 v[86:87], v[86:87], 0, v[146:147]
	v_mul_f32_e32 v78, v82, v78
	v_mul_f32_e32 v82, 0xbfb8aa3b, v83
	v_exp_f32_e32 v82, v82
	s_nop 0
	v_add_f32_e32 v82, 1.0, v82
	v_rcp_f32_e32 v82, v82
	s_nop 0
	v_mul_f32_e32 v79, v82, v79
	v_cvt_pk_bf16_f32 v78, v78, v79
	v_mul_f32_e32 v79, 0xbfb8aa3b, v84
	v_exp_f32_e32 v79, v79
	s_nop 0
	v_add_f32_e32 v79, 1.0, v79
	v_rcp_f32_e32 v79, v79
	s_nop 0
	v_mul_f32_e32 v79, v79, v80
	v_mul_f32_e32 v80, 0xbfb8aa3b, v85
	v_exp_f32_e32 v80, v80
	s_nop 0
	v_add_f32_e32 v80, 1.0, v80
	v_rcp_f32_e32 v80, v80
	s_nop 0
	v_mul_f32_e32 v80, v80, v81
	v_cvt_pk_bf16_f32 v79, v79, v80
	v_mul_f32_e32 v80, 0xbfb8aa3b, v74
	v_exp_f32_e32 v80, v80
	s_nop 0
	v_add_f32_e32 v74, 1.0, v80
	v_rcp_f32_e32 v74, v74
	s_nop 0
	v_mul_f32_e32 v70, v74, v70
	v_mul_f32_e32 v74, 0xbfb8aa3b, v75
	v_exp_f32_e32 v74, v74
	s_nop 0
	v_add_f32_e32 v74, 1.0, v74
	v_rcp_f32_e32 v74, v74
	s_nop 0
	v_mul_f32_e32 v71, v74, v71
	v_cvt_pk_bf16_f32 v80, v70, v71
	v_mul_f32_e32 v70, 0xbfb8aa3b, v76
	v_exp_f32_e32 v70, v70
	v_mul_f32_e32 v71, v76, v72
	v_mul_f32_e32 v72, v77, v73
	v_add_f32_e32 v70, 1.0, v70
	v_rcp_f32_e32 v70, v70
	s_nop 0
	v_mul_f32_e32 v70, v70, v71
	v_mul_f32_e32 v71, 0xbfb8aa3b, v77
	v_exp_f32_e32 v71, v71
	s_nop 0
	v_add_f32_e32 v71, 1.0, v71
	v_rcp_f32_e32 v71, v71
	s_nop 0
	v_mul_f32_e32 v71, v71, v72
	v_mul_f32_e32 v72, 0xbfb8aa3b, v66
	v_exp_f32_e32 v72, v72
	v_cvt_pk_bf16_f32 v81, v70, v71
	global_store_dwordx4 v[86:87], v[78:81], off
	v_add_u32_e32 v70, 0x80, v148
	v_add_f32_e32 v66, 1.0, v72
	v_rcp_f32_e32 v66, v66
	v_mad_i64_i32 v[70:71], s[4:5], v70, s22, v[144:145]
	v_lshl_add_u64 v[70:71], v[70:71], 0, v[146:147]
	v_mul_f32_e32 v62, v66, v62
	v_mul_f32_e32 v66, 0xbfb8aa3b, v67
	v_exp_f32_e32 v66, v66
	s_nop 0
	v_add_f32_e32 v66, 1.0, v66
	v_rcp_f32_e32 v66, v66
	s_nop 0
	v_mul_f32_e32 v63, v66, v63
	v_cvt_pk_bf16_f32 v62, v62, v63
	v_mul_f32_e32 v63, 0xbfb8aa3b, v68
	v_exp_f32_e32 v63, v63
	s_nop 0
	v_add_f32_e32 v63, 1.0, v63
	v_rcp_f32_e32 v63, v63
	s_nop 0
	v_mul_f32_e32 v63, v63, v64
	v_mul_f32_e32 v64, 0xbfb8aa3b, v69
	v_exp_f32_e32 v64, v64
	s_nop 0
	v_add_f32_e32 v64, 1.0, v64
	v_rcp_f32_e32 v64, v64
	s_nop 0
	v_mul_f32_e32 v64, v64, v65
	v_cvt_pk_bf16_f32 v63, v63, v64
	v_mul_f32_e32 v64, 0xbfb8aa3b, v58
	v_exp_f32_e32 v64, v64
	s_nop 0
	v_add_f32_e32 v58, 1.0, v64
	v_rcp_f32_e32 v58, v58
	s_nop 0
	v_mul_f32_e32 v54, v58, v54
	v_mul_f32_e32 v58, 0xbfb8aa3b, v59
	v_exp_f32_e32 v58, v58
	s_nop 0
	v_add_f32_e32 v58, 1.0, v58
	v_rcp_f32_e32 v58, v58
	s_nop 0
	v_mul_f32_e32 v55, v58, v55
	v_cvt_pk_bf16_f32 v64, v54, v55
	v_mul_f32_e32 v54, 0xbfb8aa3b, v60
	v_exp_f32_e32 v54, v54
	v_mul_f32_e32 v55, v60, v56
	v_mul_f32_e32 v56, v61, v57
	v_add_f32_e32 v54, 1.0, v54
	v_rcp_f32_e32 v54, v54
	s_nop 0
	v_mul_f32_e32 v54, v54, v55
	v_mul_f32_e32 v55, 0xbfb8aa3b, v61
	v_exp_f32_e32 v55, v55
	s_nop 0
	v_add_f32_e32 v55, 1.0, v55
	v_rcp_f32_e32 v55, v55
	s_nop 0
	v_mul_f32_e32 v55, v55, v56
	v_mul_f32_e32 v56, 0xbfb8aa3b, v50
	v_exp_f32_e32 v56, v56
	v_cvt_pk_bf16_f32 v65, v54, v55
	global_store_dwordx4 v[70:71], v[62:65], off
	v_add_u32_e32 v54, 0x90, v148
	v_add_f32_e32 v50, 1.0, v56
	v_rcp_f32_e32 v50, v50
	v_mad_i64_i32 v[54:55], s[4:5], v54, s22, v[144:145]
	v_lshl_add_u64 v[54:55], v[54:55], 0, v[146:147]
	v_mul_f32_e32 v46, v50, v46
	v_mul_f32_e32 v50, 0xbfb8aa3b, v51
	v_exp_f32_e32 v50, v50
	s_nop 0
	v_add_f32_e32 v50, 1.0, v50
; __device__ __forceinline__ unsigned cvt_pk_bf16(float lo, float hi) { unsigned r; asm volatile("v_cvt_pk_bf16_f32 %0, %1, %2" : "=v"(r) : "v"(lo), "v"(hi)); return r; }
; __device__ __forceinline__ float silu_mul(float g, float u) { const float e = __builtin_amdgcn_exp2f(-1.4426950408889634f * g); return g * u * __builtin_amdgcn_rcpf(1.0f + e); }
; #define PG8_BAR __builtin_amdgcn_s_barrier()
;     __device__ __forceinline__ void operator()(const f32x4 (&acc)[2][2][4][2], const Unit& u, int wr, int wc, int fr_, int fq_) const {
;     ...
;             for (int m = 0; m < 4; ++m) {
;                 bf16_t* rowp = O + (size_t)(row0 + ai * HALF + m * 16) * ldc + col0;
;                 const f32x4 g0 = acc[ai][0][m][0], g1 = acc[ai][0][m][1], u0 = acc[ai][1][m][0], u1 = acc[ai][1][m][1];
;                 u32x4 w;
;                 w.x = cvt_pk_bf16(silu_mul(g0[0], u0[0]), silu_mul(g0[1], u0[1])); w.y = cvt_pk_bf16(silu_mul(g0[2], u0[2]), silu_mul(g0[3], u0[3]));
;                 w.z = cvt_pk_bf16(silu_mul(g1[0], u1[0]), silu_mul(g1[1], u1[1])); w.w = cvt_pk_bf16(silu_mul(g1[2], u1[2]), silu_mul(g1[3], u1[3]));
;                 st16(rowp, w);
;             }
; template <class Epi, class Sched, bool ALIGN_EPI = false, bool SP2 = false>
; __device__ __forceinline__ void gemm_phase(PG8_LAS unsigned char* lds, const Gemm g, const Sched& S, const Epi& E) {
;     ...
;         if constexpr (ALIGN_EPI) { if (wr == 0) PG8_BAR; }
;         if constexpr (!Epi::AFTER_DRAIN) { E(acc, cur, wr, wc, fr, fq); S.done(cur); }
;         if (!has_next) break;
; #pragma unroll
;         for (int a = 0; a < 2; ++a)
; #pragma unroll
;             for (int b = 0; b < 2; ++b)
; #pragma unroll
;                 for (int m = 0; m < 4; ++m)
; #pragma unroll
;                     for (int n = 0; n < 2; ++n) acc[a][b][m][n] = (f32x4){0.f, 0.f, 0.f, 0.f};
;         cur = nxt; cA = nA; cB = nB; ++ui;
;         if constexpr (ALIGN_EPI) { if (wr == 1) PG8_BAR; }
	v_rcp_f32_e32 v50, v50
	s_nop 0
	v_mul_f32_e32 v47, v50, v47
	v_cvt_pk_bf16_f32 v46, v46, v47
	v_mul_f32_e32 v47, 0xbfb8aa3b, v52
	v_exp_f32_e32 v47, v47
	s_nop 0
	v_add_f32_e32 v47, 1.0, v47
	v_rcp_f32_e32 v47, v47
	s_nop 0
	v_mul_f32_e32 v47, v47, v48
	v_mul_f32_e32 v48, 0xbfb8aa3b, v53
	v_exp_f32_e32 v48, v48
	s_nop 0
	v_add_f32_e32 v48, 1.0, v48
	v_rcp_f32_e32 v48, v48
	s_nop 0
	v_mul_f32_e32 v48, v48, v49
	v_cvt_pk_bf16_f32 v47, v47, v48
	v_mul_f32_e32 v48, 0xbfb8aa3b, v42
	v_exp_f32_e32 v48, v48
	s_nop 0
	v_add_f32_e32 v42, 1.0, v48
	v_rcp_f32_e32 v42, v42
	s_nop 0
	v_mul_f32_e32 v38, v42, v38
	v_mul_f32_e32 v42, 0xbfb8aa3b, v43
	v_exp_f32_e32 v42, v42
	s_nop 0
	v_add_f32_e32 v42, 1.0, v42
	v_rcp_f32_e32 v42, v42
	s_nop 0
	v_mul_f32_e32 v39, v42, v39
	v_cvt_pk_bf16_f32 v48, v38, v39
	v_mul_f32_e32 v38, 0xbfb8aa3b, v44
	v_exp_f32_e32 v38, v38
	v_mul_f32_e32 v39, v44, v40
	v_mul_f32_e32 v40, v45, v41
	v_add_f32_e32 v38, 1.0, v38
	v_rcp_f32_e32 v38, v38
	s_nop 0
	v_mul_f32_e32 v38, v38, v39
	v_mul_f32_e32 v39, 0xbfb8aa3b, v45
	v_exp_f32_e32 v39, v39
	s_nop 0
	v_add_f32_e32 v39, 1.0, v39
	v_rcp_f32_e32 v39, v39
	s_nop 0
	v_mul_f32_e32 v39, v39, v40
	v_mul_f32_e32 v40, 0xbfb8aa3b, v34
	v_exp_f32_e32 v40, v40
	v_cvt_pk_bf16_f32 v49, v38, v39
	global_store_dwordx4 v[54:55], v[46:49], off
	v_add_u32_e32 v38, 0xa0, v148
	v_add_f32_e32 v34, 1.0, v40
	v_rcp_f32_e32 v34, v34
	v_mad_i64_i32 v[38:39], s[4:5], v38, s22, v[144:145]
	v_lshl_add_u64 v[38:39], v[38:39], 0, v[146:147]
	v_mul_f32_e32 v30, v34, v30
	v_mul_f32_e32 v34, 0xbfb8aa3b, v35
	v_exp_f32_e32 v34, v34
	s_nop 0
	v_add_f32_e32 v34, 1.0, v34
	v_rcp_f32_e32 v34, v34
	s_nop 0
	v_mul_f32_e32 v31, v34, v31
	v_cvt_pk_bf16_f32 v30, v30, v31
	v_mul_f32_e32 v31, 0xbfb8aa3b, v36
	v_exp_f32_e32 v31, v31
	s_nop 0
	v_add_f32_e32 v31, 1.0, v31
	v_rcp_f32_e32 v31, v31
	s_nop 0
	v_mul_f32_e32 v31, v31, v32
	v_mul_f32_e32 v32, 0xbfb8aa3b, v37
	v_exp_f32_e32 v32, v32
	s_nop 0
	v_add_f32_e32 v32, 1.0, v32
	v_rcp_f32_e32 v32, v32
	s_nop 0
	v_mul_f32_e32 v32, v32, v33
	v_cvt_pk_bf16_f32 v31, v31, v32
	v_mul_f32_e32 v32, 0xbfb8aa3b, v26
	v_exp_f32_e32 v32, v32
	s_nop 0
	v_add_f32_e32 v26, 1.0, v32
	v_rcp_f32_e32 v26, v26
	s_nop 0
	v_mul_f32_e32 v22, v26, v22
	v_mul_f32_e32 v26, 0xbfb8aa3b, v27
	v_exp_f32_e32 v26, v26
	s_nop 0
	v_add_f32_e32 v26, 1.0, v26
	v_rcp_f32_e32 v26, v26
	s_nop 0
	v_mul_f32_e32 v23, v26, v23
	v_cvt_pk_bf16_f32 v32, v22, v23
	v_mul_f32_e32 v22, 0xbfb8aa3b, v28
	v_exp_f32_e32 v22, v22
	v_mul_f32_e32 v23, v28, v24
	v_mul_f32_e32 v24, v29, v25
	v_add_f32_e32 v22, 1.0, v22
	v_rcp_f32_e32 v22, v22
	s_nop 0
	v_mul_f32_e32 v22, v22, v23
	v_mul_f32_e32 v23, 0xbfb8aa3b, v29
	v_exp_f32_e32 v23, v23
	s_nop 0
	v_add_f32_e32 v23, 1.0, v23
	v_rcp_f32_e32 v23, v23
	s_nop 0
	v_mul_f32_e32 v23, v23, v24
	v_mul_f32_e32 v24, 0xbfb8aa3b, v18
	v_exp_f32_e32 v24, v24
	v_cvt_pk_bf16_f32 v33, v22, v23
	global_store_dwordx4 v[38:39], v[30:33], off
	v_add_u32_e32 v22, 0xb0, v148
	v_add_f32_e32 v18, 1.0, v24
	v_rcp_f32_e32 v18, v18
	v_mad_i64_i32 v[22:23], s[4:5], v22, s22, v[144:145]
	v_lshl_add_u64 v[22:23], v[22:23], 0, v[146:147]
	v_mul_f32_e32 v10, v18, v10
	v_mul_f32_e32 v18, 0xbfb8aa3b, v19
	v_exp_f32_e32 v18, v18
	s_mov_b64 s[4:5], -1
	v_add_f32_e32 v18, 1.0, v18
	v_rcp_f32_e32 v18, v18
	s_nop 0
	v_mul_f32_e32 v11, v18, v11
	v_cvt_pk_bf16_f32 v10, v10, v11
	v_mul_f32_e32 v11, 0xbfb8aa3b, v20
	v_exp_f32_e32 v11, v11
	s_nop 0
	v_add_f32_e32 v11, 1.0, v11
	v_rcp_f32_e32 v11, v11
	s_nop 0
	v_mul_f32_e32 v11, v11, v12
	v_mul_f32_e32 v12, 0xbfb8aa3b, v21
	v_exp_f32_e32 v12, v12
	s_nop 0
	v_add_f32_e32 v12, 1.0, v12
	v_rcp_f32_e32 v12, v12
	s_nop 0
	v_mul_f32_e32 v12, v12, v13
	v_cvt_pk_bf16_f32 v11, v11, v12
	v_mul_f32_e32 v12, 0xbfb8aa3b, v6
	v_exp_f32_e32 v12, v12
	s_nop 0
	v_add_f32_e32 v6, 1.0, v12
	v_rcp_f32_e32 v6, v6
	s_nop 0
	v_mul_f32_e32 v2, v6, v2
	v_mul_f32_e32 v6, 0xbfb8aa3b, v7
	v_exp_f32_e32 v6, v6
	s_nop 0
	v_add_f32_e32 v6, 1.0, v6
	v_rcp_f32_e32 v6, v6
	s_nop 0
	v_mul_f32_e32 v3, v6, v3
	v_cvt_pk_bf16_f32 v12, v2, v3
	v_mul_f32_e32 v2, 0xbfb8aa3b, v8
	v_exp_f32_e32 v2, v2
	v_mul_f32_e32 v3, v8, v4
	v_mul_f32_e32 v4, v9, v5
	v_add_f32_e32 v2, 1.0, v2
	v_rcp_f32_e32 v2, v2
	s_nop 0
	v_mul_f32_e32 v2, v2, v3
	v_mul_f32_e32 v3, 0xbfb8aa3b, v9
	v_exp_f32_e32 v3, v3
	s_nop 0
	v_add_f32_e32 v3, 1.0, v3
	v_rcp_f32_e32 v3, v3
	s_nop 0
	v_mul_f32_e32 v3, v3, v4
	v_cvt_pk_bf16_f32 v13, v2, v3
	global_store_dwordx4 v[22:23], v[10:13], off
	s_cbranch_vccnz .LBB0_394
	s_andn2_b64 vcc, exec, s[12:13]
	s_cbranch_vccnz .LBB0_393
	s_barrier
	s_branch .LBB0_393
